# E30: E27 + P0 order mix (half of the WGs convert weights first, window copy second)
# baseline (speedup 1.0000x reference)
.LBB0_5:
	s_or_b64 exec, exec, s[0:1]
	s_load_dwordx2 s[0:1], s[78:79], 0x2a8
	v_lshl_or_b32 v0, s76, 9, v248
	s_waitcnt lgkmcnt(0)
	s_cmp_lt_i32 s0, 1
	s_cselect_b64 s[10:11], -1, 0
	s_cmp_gt_i32 s1, 0
	s_cselect_b64 s[0:1], -1, 0
	s_and_b64 s[0:1], s[10:11], s[0:1]
	s_andn2_b64 vcc, exec, s[0:1]
	s_cbranch_vccnz .LBB0_232
	s_mov_b32 s101, 0
	s_bitcmp1_b32 s76, 3
	s_cbranch_scc0 .Lmy_p0_norm
	s_load_dword s33, s[78:79], 0x2b0
	v_lshlrev_b32_e32 v32, 2, v248
	v_lshrrev_b32_e32 v1, 6, v248
	s_mov_b32 s101, 1
	s_waitcnt lgkmcnt(0)
	s_branch .Lmy_p0_cvt
.Lmy_p0_norm:
	s_load_dword s33, s[78:79], 0x2b0
	s_mov_b32 s0, 0x5328f5
	v_lshl_or_b32 v34, s76, 9, v248
	s_waitcnt lgkmcnt(0)
	s_cmp_gt_i32 s33, 56
	s_cselect_b32 s6, s0, 0x7e0000
	v_cmp_le_u32_e32 vcc, s6, v34
	s_and_saveexec_b64 s[0:1], vcc
	s_xor_b64 s[0:1], exec, s[0:1]
	s_cbranch_execz .LBB0_9
	v_lshlrev_b32_e32 v32, 2, v248
	s_or_saveexec_b64 s[0:1], s[0:1]
	s_lshl_b32 s12, s33, 9
	s_xor_b64 exec, exec, s[0:1]
	s_cbranch_execnz .LBB0_10

.LBB0_27:
	s_cmp_eq_u32 s101, 2
	s_cbranch_scc1 .LBB0_204

.LBB0_204:
	s_cmp_eq_u32 s101, 1
	s_cbranch_scc0 .Lmy_p0_rest
	s_mov_b32 s101, 2
	s_branch .Lmy_p0_norm
